# v11 + GEMM9 final-norm exchange made data-tagged: partials published with the (always clear) sign bit set, readers poll the slots and use |x|; arrival counter, store-ack wait and slot re-read removed
# speedup vs baseline: 1.0072x; 1.0072x over previous
;     __device__ __forceinline__ void operator()(const f32x4 (&acc_)[2][2][4][2], const pg8::Unit& u, int wr, int wc, int fr, int fq) const {
;     ...
;         const int row0 = u.pm * 256 + wr * 64 + fr, col0 = u.pn * 256 + wc * 32 + 8 * fq, lane = threadIdx.x & 63;
; #pragma unroll
;         for (int ai = 0; ai < 2; ++ai)
; #pragma unroll
;             for (int m = 0; m < 4; ++m) {
;                 const int row = row0 + ai * 128 + m * 16; float ss = 0.f;
; #pragma unroll
;                 for (int bj = 0; bj < 2; ++bj) {
;                     const size_t off = (size_t)row * D + col0 + bj * 128;
;                     const u32x4 r = *(const u32x4*)(resb + off);
;                     const f32x4 x0 = (f32x4){__builtin_bit_cast(float, r.x << 16), __builtin_bit_cast(float, r.x & 0xffff0000u), __builtin_bit_cast(float, r.y << 16), __builtin_bit_cast(float, r.y & 0xffff0000u)};
;                     const f32x4 x1 = (f32x4){__builtin_bit_cast(float, r.z << 16), __builtin_bit_cast(float, r.z & 0xffff0000u), __builtin_bit_cast(float, r.w << 16), __builtin_bit_cast(float, r.w & 0xffff0000u)};
;                     const f32x4 v0 = x0 + A[ai][bj][m][0] * 0.5f, v1 = x1 + A[ai][bj][m][1] * 0.5f;
;                     A[ai][bj][m][0] = v0; A[ai][bj][m][1] = v1;
;                     ss += ((v0[0] * v0[0] + v0[1] * v0[1]) + (v0[2] * v0[2] + v0[3] * v0[3])) + ((v1[0] * v1[0] + v1[1] * v1[1]) + (v1[2] * v1[2] + v1[3] * v1[3]));
;                 }
;                 ss += __shfl_xor(ss, 16); ss += __shfl_xor(ss, 32);
;                 if (fq == 0) __hip_atomic_store(xch + (size_t)row * 16 + u.pn * 4 + wc, ss, __ATOMIC_RELAXED, __HIP_MEMORY_SCOPE_AGENT);
.LBB0_959:
	v_lshl_add_u32 v146, s62, 8, v196
	v_ashrrev_i32_e32 v147, 31, v146
	v_lshl_or_b32 v148, s63, 8, v199
	v_lshlrev_b64 v[150:151], 11, v[146:147]
	v_ashrrev_i32_e32 v149, 31, v148
	v_lshl_add_u64 v[150:151], s[44:45], 0, v[150:151]
	v_lshl_add_u64 v[154:155], v[148:149], 1, v[150:151]
	v_mov_b64_e32 v[248:249], v[154:155]
	global_load_dwordx4 v[214:217], v[248:249], off
	global_load_dwordx4 v[218:221], v[248:249], off offset:256
	s_mov_b32 s36, 0x8000
	s_mov_b32 s37, 0
	v_lshl_add_u64 v[226:227], v[248:249], 0, s[36:37]
	global_load_dwordx4 v[222:225], v[226:227], off
	s_nop 0
	global_load_dwordx4 v[226:229], v[226:227], off offset:256
	s_mov_b32 s36, 0x10000
	s_mov_b32 s37, 0
	v_lshl_add_u64 v[234:235], v[248:249], 0, s[36:37]
	global_load_dwordx4 v[230:233], v[234:235], off
	s_nop 0
	global_load_dwordx4 v[234:237], v[234:235], off offset:256
	s_mov_b32 s36, 0x18000
	s_mov_b32 s37, 0
	v_lshl_add_u64 v[242:243], v[248:249], 0, s[36:37]
	global_load_dwordx4 v[238:241], v[242:243], off
	s_nop 0
	global_load_dwordx4 v[242:245], v[242:243], off offset:256
	v_and_b32_e32 v159, 64, v203
	v_xor_b32_e32 v158, 16, v203
	v_add_u32_e32 v166, 64, v159
	v_cmp_lt_i32_e32 vcc, v158, v166
	s_lshl_b32 s30, s63, 2
	s_ashr_i32 s31, s30, 31
	v_cndmask_b32_e32 v158, v203, v158, vcc
	v_lshlrev_b32_e32 v205, 2, v158
	s_waitcnt vmcnt(6)
	v_lshlrev_b32_e32 v158, 16, v214
	v_and_b32_e32 v159, 0xffff0000, v214
	v_lshlrev_b32_e32 v150, 16, v215
	v_and_b32_e32 v151, 0xffff0000, v215
	v_lshlrev_b32_e32 v160, 16, v216
	v_and_b32_e32 v161, 0xffff0000, v216
	v_lshlrev_b32_e32 v152, 16, v217
	v_and_b32_e32 v153, 0xffff0000, v217
	v_lshlrev_b32_e32 v162, 16, v218
	v_and_b32_e32 v163, 0xffff0000, v218
	v_lshlrev_b32_e32 v154, 16, v219
	v_and_b32_e32 v155, 0xffff0000, v219
	v_lshlrev_b32_e32 v164, 16, v220
	v_and_b32_e32 v165, 0xffff0000, v220
	v_lshlrev_b32_e32 v156, 16, v221
	v_and_b32_e32 v157, 0xffff0000, v221
	s_mov_b32 s36, 0x40000
	s_mov_b32 s37, 0
	v_lshl_add_u64 v[218:219], v[248:249], 0, s[36:37]
	global_load_dwordx4 v[214:217], v[218:219], off
	s_nop 0
	global_load_dwordx4 v[218:221], v[218:219], off offset:256
	v_pk_fma_f32 v[126:127], v[126:127], 0.5, v[150:151] op_sel_hi:[1,0,1]
	v_pk_fma_f32 v[124:125], v[124:125], 0.5, v[158:159] op_sel_hi:[1,0,1]
	v_pk_fma_f32 v[122:123], v[122:123], 0.5, v[152:153] op_sel_hi:[1,0,1]
	v_pk_fma_f32 v[120:121], v[120:121], 0.5, v[160:161] op_sel_hi:[1,0,1]
	v_pk_fma_f32 v[118:119], v[118:119], 0.5, v[154:155] op_sel_hi:[1,0,1]
	v_pk_fma_f32 v[116:117], v[116:117], 0.5, v[162:163] op_sel_hi:[1,0,1]
	v_pk_fma_f32 v[114:115], v[114:115], 0.5, v[156:157] op_sel_hi:[1,0,1]
	v_pk_fma_f32 v[112:113], v[112:113], 0.5, v[164:165] op_sel_hi:[1,0,1]
	v_mul_f32_e32 v150, v125, v125
	v_mul_f32_e32 v151, v127, v127
	v_mul_f32_e32 v152, v121, v121
	v_mul_f32_e32 v153, v123, v123
	v_mul_f32_e32 v154, v117, v117
	v_mul_f32_e32 v155, v119, v119
	v_mul_f32_e32 v156, v113, v113
	v_mul_f32_e32 v157, v115, v115
	v_fmac_f32_e32 v150, v124, v124
	v_fmac_f32_e32 v151, v126, v126
	v_fmac_f32_e32 v152, v120, v120
	v_fmac_f32_e32 v153, v122, v122
	v_fmac_f32_e32 v154, v116, v116
	v_fmac_f32_e32 v155, v118, v118
	v_fmac_f32_e32 v156, v112, v112
	v_fmac_f32_e32 v157, v114, v114
	v_add_f32_e32 v150, v150, v151
	v_add_f32_e32 v151, v152, v153
	v_add_f32_e32 v152, v154, v155
	v_add_f32_e32 v153, v156, v157
	v_add_f32_e32 v150, v150, v151
	v_add_f32_e32 v151, v152, v153
	v_add_f32_e32 v150, v150, v151
	ds_bpermute_b32 v151, v205, v150
	v_xor_b32_e32 v152, 32, v203
	v_cmp_lt_i32_e32 vcc, v152, v166
	v_lshlrev_b64 v[156:157], 6, v[146:147]
	s_waitcnt lgkmcnt(0)
	v_add_f32_e32 v150, v150, v151
	v_cndmask_b32_e32 v152, v203, v152, vcc
	v_lshlrev_b32_e32 v206, 2, v152
	ds_bpermute_b32 v151, v206, v150
	s_and_saveexec_b64 s[34:35], s[0:1]
	s_cbranch_execz .LBB0_961
	s_waitcnt lgkmcnt(0)
	v_add_f32_e32 v152, v150, v151
	v_lshl_add_u64 v[150:151], s[48:49], 0, v[156:157]
	v_lshl_add_u64 v[150:151], s[30:31], 2, v[150:151]
	s_lshl_b32 s36, s53, 2
	s_mov_b32 s37, s21
	v_lshl_add_u64 v[150:151], v[150:151], 0, s[36:37]
	v_or_b32_e32 v152, 0x80000000, v152
	global_store_dword v[150:151], v152, off sc1
.LBB0_961:
	s_or_b64 exec, exec, s[34:35]
	v_or_b32_e32 v150, 16, v146
	s_waitcnt lgkmcnt(0)
	v_ashrrev_i32_e32 v151, 31, v150
	v_lshlrev_b64 v[152:153], 11, v[150:151]
	v_lshl_add_u64 v[152:153], s[44:45], 0, v[152:153]
	v_lshl_add_u64 v[158:159], v[148:149], 1, v[152:153]
	s_waitcnt vmcnt(7)
	v_lshlrev_b32_e32 v162, 16, v222
	v_and_b32_e32 v163, 0xffff0000, v222
	v_lshlrev_b32_e32 v152, 16, v223
	v_and_b32_e32 v153, 0xffff0000, v223
	v_lshlrev_b32_e32 v164, 16, v224
	v_and_b32_e32 v165, 0xffff0000, v224
	v_lshlrev_b32_e32 v154, 16, v225
	v_and_b32_e32 v155, 0xffff0000, v225
	v_lshlrev_b32_e32 v166, 16, v226
	v_and_b32_e32 v167, 0xffff0000, v226
	v_lshlrev_b32_e32 v158, 16, v227
	v_and_b32_e32 v159, 0xffff0000, v227
	v_lshlrev_b32_e32 v168, 16, v228
	v_and_b32_e32 v169, 0xffff0000, v228
	v_lshlrev_b32_e32 v160, 16, v229
	v_and_b32_e32 v161, 0xffff0000, v229
	s_mov_b32 s36, 0x48000
	s_mov_b32 s37, 0
	v_lshl_add_u64 v[226:227], v[248:249], 0, s[36:37]
	global_load_dwordx4 v[222:225], v[226:227], off
	s_nop 0
	global_load_dwordx4 v[226:229], v[226:227], off offset:256
	v_pk_fma_f32 v[110:111], v[110:111], 0.5, v[152:153] op_sel_hi:[1,0,1]
	v_pk_fma_f32 v[108:109], v[108:109], 0.5, v[162:163] op_sel_hi:[1,0,1]
	v_pk_fma_f32 v[106:107], v[106:107], 0.5, v[154:155] op_sel_hi:[1,0,1]
	v_pk_fma_f32 v[104:105], v[104:105], 0.5, v[164:165] op_sel_hi:[1,0,1]
	v_pk_fma_f32 v[102:103], v[102:103], 0.5, v[158:159] op_sel_hi:[1,0,1]
	v_pk_fma_f32 v[100:101], v[100:101], 0.5, v[166:167] op_sel_hi:[1,0,1]
	v_pk_fma_f32 v[98:99], v[98:99], 0.5, v[160:161] op_sel_hi:[1,0,1]
	v_pk_fma_f32 v[96:97], v[96:97], 0.5, v[168:169] op_sel_hi:[1,0,1]
	v_mul_f32_e32 v152, v109, v109
	v_mul_f32_e32 v153, v111, v111
	v_mul_f32_e32 v154, v105, v105
	v_mul_f32_e32 v155, v107, v107
	v_mul_f32_e32 v158, v101, v101
	v_mul_f32_e32 v159, v103, v103
	v_mul_f32_e32 v160, v97, v97
	v_mul_f32_e32 v161, v99, v99
	v_fmac_f32_e32 v152, v108, v108
	v_fmac_f32_e32 v153, v110, v110
	v_fmac_f32_e32 v154, v104, v104
	v_fmac_f32_e32 v155, v106, v106
	v_fmac_f32_e32 v158, v100, v100
	v_fmac_f32_e32 v159, v102, v102
	v_fmac_f32_e32 v160, v96, v96
	v_fmac_f32_e32 v161, v98, v98
	v_add_f32_e32 v152, v152, v153
	v_add_f32_e32 v153, v154, v155
	v_add_f32_e32 v154, v158, v159
	v_add_f32_e32 v155, v160, v161
	v_add_f32_e32 v152, v152, v153
	v_add_f32_e32 v153, v154, v155
	v_add_f32_e32 v152, v152, v153
	ds_bpermute_b32 v153, v205, v152
	v_lshlrev_b64 v[160:161], 6, v[150:151]
	s_waitcnt lgkmcnt(0)
	v_add_f32_e32 v152, v152, v153
	ds_bpermute_b32 v153, v206, v152
	s_and_saveexec_b64 s[34:35], s[0:1]
	s_cbranch_execz .LBB0_963
;     __device__ __forceinline__ void operator()(const f32x4 (&acc_)[2][2][4][2], const pg8::Unit& u, int wr, int wc, int fr, int fq) const {
;     ...
;                 const int row = row0 + ai * 128 + m * 16; float ss = 0.f;
; #pragma unroll
;                 for (int bj = 0; bj < 2; ++bj) {
;                     const size_t off = (size_t)row * D + col0 + bj * 128;
;                     const u32x4 r = *(const u32x4*)(resb + off);
;                     const f32x4 x0 = (f32x4){__builtin_bit_cast(float, r.x << 16), __builtin_bit_cast(float, r.x & 0xffff0000u), __builtin_bit_cast(float, r.y << 16), __builtin_bit_cast(float, r.y & 0xffff0000u)};
;                     const f32x4 x1 = (f32x4){__builtin_bit_cast(float, r.z << 16), __builtin_bit_cast(float, r.z & 0xffff0000u), __builtin_bit_cast(float, r.w << 16), __builtin_bit_cast(float, r.w & 0xffff0000u)};
;                     const f32x4 v0 = x0 + A[ai][bj][m][0] * 0.5f, v1 = x1 + A[ai][bj][m][1] * 0.5f;
;                     A[ai][bj][m][0] = v0; A[ai][bj][m][1] = v1;
;                     ss += ((v0[0] * v0[0] + v0[1] * v0[1]) + (v0[2] * v0[2] + v0[3] * v0[3])) + ((v1[0] * v1[0] + v1[1] * v1[1]) + (v1[2] * v1[2] + v1[3] * v1[3]));
;                 }
;                 ss += __shfl_xor(ss, 16); ss += __shfl_xor(ss, 32);
;                 if (fq == 0) __hip_atomic_store(xch + (size_t)row * 16 + u.pn * 4 + wc, ss, __ATOMIC_RELAXED, __HIP_MEMORY_SCOPE_AGENT);
	s_waitcnt lgkmcnt(0)
	v_add_f32_e32 v154, v152, v153
	v_lshl_add_u64 v[152:153], s[48:49], 0, v[160:161]
	v_lshl_add_u64 v[152:153], s[30:31], 2, v[152:153]
	s_lshl_b32 s36, s53, 2
	s_mov_b32 s37, s21
	v_lshl_add_u64 v[152:153], v[152:153], 0, s[36:37]
	v_or_b32_e32 v154, 0x80000000, v154
	global_store_dword v[152:153], v154, off sc1
.LBB0_963:
	s_or_b64 exec, exec, s[34:35]
	v_or_b32_e32 v152, 32, v146
	s_waitcnt lgkmcnt(0)
	v_ashrrev_i32_e32 v153, 31, v152
	v_lshlrev_b64 v[154:155], 11, v[152:153]
	v_lshl_add_u64 v[154:155], s[44:45], 0, v[154:155]
	v_lshl_add_u64 v[154:155], v[148:149], 1, v[154:155]
	s_waitcnt vmcnt(8)
	v_lshlrev_b32_e32 v154, 16, v230
	v_and_b32_e32 v155, 0xffff0000, v230
	v_lshlrev_b32_e32 v158, 16, v231
	v_and_b32_e32 v159, 0xffff0000, v231
	v_lshlrev_b32_e32 v162, 16, v232
	v_and_b32_e32 v163, 0xffff0000, v232
	v_lshlrev_b32_e32 v164, 16, v233
	v_and_b32_e32 v165, 0xffff0000, v233
	v_lshlrev_b32_e32 v170, 16, v234
	v_and_b32_e32 v171, 0xffff0000, v234
	v_lshlrev_b32_e32 v166, 16, v235
	v_and_b32_e32 v167, 0xffff0000, v235
	v_lshlrev_b32_e32 v172, 16, v236
	v_and_b32_e32 v173, 0xffff0000, v236
	v_lshlrev_b32_e32 v168, 16, v237
	v_and_b32_e32 v169, 0xffff0000, v237
	s_mov_b32 s36, 0x50000
	s_mov_b32 s37, 0
	v_lshl_add_u64 v[234:235], v[248:249], 0, s[36:37]
	global_load_dwordx4 v[230:233], v[234:235], off
	s_nop 0
	global_load_dwordx4 v[234:237], v[234:235], off offset:256
	v_pk_fma_f32 v[94:95], v[94:95], 0.5, v[158:159] op_sel_hi:[1,0,1]
	v_pk_fma_f32 v[92:93], v[92:93], 0.5, v[154:155] op_sel_hi:[1,0,1]
	v_pk_fma_f32 v[90:91], v[90:91], 0.5, v[164:165] op_sel_hi:[1,0,1]
	v_pk_fma_f32 v[88:89], v[88:89], 0.5, v[162:163] op_sel_hi:[1,0,1]
	v_pk_fma_f32 v[86:87], v[86:87], 0.5, v[166:167] op_sel_hi:[1,0,1]
	v_pk_fma_f32 v[84:85], v[84:85], 0.5, v[170:171] op_sel_hi:[1,0,1]
	v_pk_fma_f32 v[82:83], v[82:83], 0.5, v[168:169] op_sel_hi:[1,0,1]
	v_pk_fma_f32 v[80:81], v[80:81], 0.5, v[172:173] op_sel_hi:[1,0,1]
	v_mul_f32_e32 v154, v93, v93
	v_mul_f32_e32 v155, v95, v95
	v_mul_f32_e32 v158, v89, v89
	v_mul_f32_e32 v159, v91, v91
	v_mul_f32_e32 v162, v85, v85
	v_mul_f32_e32 v163, v87, v87
	v_mul_f32_e32 v164, v81, v81
	v_mul_f32_e32 v165, v83, v83
	v_fmac_f32_e32 v154, v92, v92
	v_fmac_f32_e32 v155, v94, v94
	v_fmac_f32_e32 v158, v88, v88
	v_fmac_f32_e32 v159, v90, v90
	v_fmac_f32_e32 v162, v84, v84
	v_fmac_f32_e32 v163, v86, v86
	v_fmac_f32_e32 v164, v80, v80
	v_fmac_f32_e32 v165, v82, v82
	v_add_f32_e32 v154, v154, v155
	v_add_f32_e32 v155, v158, v159
	v_add_f32_e32 v158, v162, v163
	v_add_f32_e32 v159, v164, v165
	v_add_f32_e32 v154, v154, v155
	v_add_f32_e32 v155, v158, v159
	v_add_f32_e32 v154, v154, v155
	ds_bpermute_b32 v155, v205, v154
	v_lshlrev_b64 v[164:165], 6, v[152:153]
	s_waitcnt lgkmcnt(0)
	v_add_f32_e32 v154, v154, v155
	ds_bpermute_b32 v155, v206, v154
	s_and_saveexec_b64 s[34:35], s[0:1]
	s_cbranch_execz .LBB0_965
	s_waitcnt lgkmcnt(0)
	v_add_f32_e32 v158, v154, v155
	v_lshl_add_u64 v[154:155], s[48:49], 0, v[164:165]
	v_lshl_add_u64 v[154:155], s[30:31], 2, v[154:155]
	s_lshl_b32 s36, s53, 2
	s_mov_b32 s37, s21
	v_lshl_add_u64 v[154:155], v[154:155], 0, s[36:37]
	v_or_b32_e32 v158, 0x80000000, v158
	global_store_dword v[154:155], v158, off sc1
.LBB0_965:
	s_or_b64 exec, exec, s[34:35]
	v_or_b32_e32 v154, 48, v146
	s_waitcnt lgkmcnt(0)
	v_ashrrev_i32_e32 v155, 31, v154
	v_lshlrev_b64 v[158:159], 11, v[154:155]
	v_lshl_add_u64 v[158:159], s[44:45], 0, v[158:159]
	v_lshl_add_u64 v[158:159], v[148:149], 1, v[158:159]
	s_waitcnt vmcnt(9)
	v_lshlrev_b32_e32 v158, 16, v238
	v_and_b32_e32 v159, 0xffff0000, v238
	v_lshlrev_b32_e32 v162, 16, v239
	v_and_b32_e32 v163, 0xffff0000, v239
	v_lshlrev_b32_e32 v166, 16, v240
	v_and_b32_e32 v167, 0xffff0000, v240
	v_lshlrev_b32_e32 v168, 16, v241
	v_and_b32_e32 v169, 0xffff0000, v241
	v_lshlrev_b32_e32 v174, 16, v242
	v_and_b32_e32 v175, 0xffff0000, v242
	v_lshlrev_b32_e32 v170, 16, v243
	v_and_b32_e32 v171, 0xffff0000, v243
	v_lshlrev_b32_e32 v176, 16, v244
	v_and_b32_e32 v177, 0xffff0000, v244
	v_lshlrev_b32_e32 v172, 16, v245
	v_and_b32_e32 v173, 0xffff0000, v245
	s_mov_b32 s36, 0x58000
	s_mov_b32 s37, 0
	v_lshl_add_u64 v[242:243], v[248:249], 0, s[36:37]
	global_load_dwordx4 v[238:241], v[242:243], off
	s_nop 0
	global_load_dwordx4 v[242:245], v[242:243], off offset:256
	v_pk_fma_f32 v[78:79], v[78:79], 0.5, v[162:163] op_sel_hi:[1,0,1]
	v_pk_fma_f32 v[76:77], v[76:77], 0.5, v[158:159] op_sel_hi:[1,0,1]
	v_pk_fma_f32 v[74:75], v[74:75], 0.5, v[168:169] op_sel_hi:[1,0,1]
	v_pk_fma_f32 v[72:73], v[72:73], 0.5, v[166:167] op_sel_hi:[1,0,1]
	v_pk_fma_f32 v[70:71], v[70:71], 0.5, v[170:171] op_sel_hi:[1,0,1]
	v_pk_fma_f32 v[68:69], v[68:69], 0.5, v[174:175] op_sel_hi:[1,0,1]
	v_pk_fma_f32 v[66:67], v[66:67], 0.5, v[172:173] op_sel_hi:[1,0,1]
	v_pk_fma_f32 v[64:65], v[64:65], 0.5, v[176:177] op_sel_hi:[1,0,1]
	v_mul_f32_e32 v158, v77, v77
	v_mul_f32_e32 v159, v79, v79
	v_mul_f32_e32 v162, v73, v73
	v_mul_f32_e32 v163, v75, v75
	v_mul_f32_e32 v166, v69, v69
	v_mul_f32_e32 v167, v71, v71
	v_mul_f32_e32 v168, v65, v65
	v_mul_f32_e32 v169, v67, v67
	v_fmac_f32_e32 v158, v76, v76
	v_fmac_f32_e32 v159, v78, v78
	v_fmac_f32_e32 v162, v72, v72
	v_fmac_f32_e32 v163, v74, v74
	v_fmac_f32_e32 v166, v68, v68
	v_fmac_f32_e32 v167, v70, v70
	v_fmac_f32_e32 v168, v64, v64
	v_fmac_f32_e32 v169, v66, v66
	v_add_f32_e32 v158, v158, v159
	v_add_f32_e32 v159, v162, v163
	v_add_f32_e32 v162, v166, v167
	v_add_f32_e32 v163, v168, v169
	v_add_f32_e32 v158, v158, v159
	v_add_f32_e32 v159, v162, v163
	v_add_f32_e32 v158, v158, v159
	ds_bpermute_b32 v159, v205, v158
	v_lshlrev_b64 v[168:169], 6, v[154:155]
	s_waitcnt lgkmcnt(0)
	v_add_f32_e32 v158, v158, v159
	ds_bpermute_b32 v159, v206, v158
	s_and_saveexec_b64 s[34:35], s[0:1]
	s_cbranch_execz .LBB0_967
	s_waitcnt lgkmcnt(0)
	v_add_f32_e32 v162, v158, v159
	v_lshl_add_u64 v[158:159], s[48:49], 0, v[168:169]
	v_lshl_add_u64 v[158:159], s[30:31], 2, v[158:159]
	s_lshl_b32 s36, s53, 2
	s_mov_b32 s37, s21
	v_lshl_add_u64 v[158:159], v[158:159], 0, s[36:37]
	v_or_b32_e32 v162, 0x80000000, v162
	global_store_dword v[158:159], v162, off sc1
;     __device__ __forceinline__ void operator()(const f32x4 (&acc_)[2][2][4][2], const pg8::Unit& u, int wr, int wc, int fr, int fq) const {
;     ...
;                 const int row = row0 + ai * 128 + m * 16; float ss = 0.f;
; #pragma unroll
;                 for (int bj = 0; bj < 2; ++bj) {
;                     const size_t off = (size_t)row * D + col0 + bj * 128;
;                     const u32x4 r = *(const u32x4*)(resb + off);
;                     const f32x4 x0 = (f32x4){__builtin_bit_cast(float, r.x << 16), __builtin_bit_cast(float, r.x & 0xffff0000u), __builtin_bit_cast(float, r.y << 16), __builtin_bit_cast(float, r.y & 0xffff0000u)};
;                     const f32x4 x1 = (f32x4){__builtin_bit_cast(float, r.z << 16), __builtin_bit_cast(float, r.z & 0xffff0000u), __builtin_bit_cast(float, r.w << 16), __builtin_bit_cast(float, r.w & 0xffff0000u)};
;                     const f32x4 v0 = x0 + A[ai][bj][m][0] * 0.5f, v1 = x1 + A[ai][bj][m][1] * 0.5f;
;                     A[ai][bj][m][0] = v0; A[ai][bj][m][1] = v1;
;                     ss += ((v0[0] * v0[0] + v0[1] * v0[1]) + (v0[2] * v0[2] + v0[3] * v0[3])) + ((v1[0] * v1[0] + v1[1] * v1[1]) + (v1[2] * v1[2] + v1[3] * v1[3]));
;                 }
;                 ss += __shfl_xor(ss, 16); ss += __shfl_xor(ss, 32);
;                 if (fq == 0) __hip_atomic_store(xch + (size_t)row * 16 + u.pn * 4 + wc, ss, __ATOMIC_RELAXED, __HIP_MEMORY_SCOPE_AGENT);
.LBB0_967:
	s_or_b64 exec, exec, s[34:35]
	v_add_u32_e32 v158, 0x80, v146
	s_waitcnt lgkmcnt(0)
	v_ashrrev_i32_e32 v159, 31, v158
	v_lshlrev_b64 v[162:163], 11, v[158:159]
	v_lshl_add_u64 v[162:163], s[44:45], 0, v[162:163]
	v_lshl_add_u64 v[162:163], v[148:149], 1, v[162:163]
	v_lshlrev_b64 v[186:187], 6, v[158:159]
	s_waitcnt vmcnt(10)
	v_lshlrev_b32_e32 v162, 16, v214
	v_and_b32_e32 v163, 0xffff0000, v214
	v_lshlrev_b32_e32 v166, 16, v215
	v_and_b32_e32 v167, 0xffff0000, v215
	v_lshlrev_b32_e32 v170, 16, v216
	v_and_b32_e32 v171, 0xffff0000, v216
	v_lshlrev_b32_e32 v172, 16, v217
	v_and_b32_e32 v173, 0xffff0000, v217
	v_lshlrev_b32_e32 v178, 16, v218
	v_and_b32_e32 v179, 0xffff0000, v218
	v_lshlrev_b32_e32 v174, 16, v219
	v_and_b32_e32 v175, 0xffff0000, v219
	v_lshlrev_b32_e32 v180, 16, v220
	v_and_b32_e32 v181, 0xffff0000, v220
	v_lshlrev_b32_e32 v176, 16, v221
	v_and_b32_e32 v177, 0xffff0000, v221
	v_pk_fma_f32 v[62:63], v[62:63], 0.5, v[166:167] op_sel_hi:[1,0,1]
	v_pk_fma_f32 v[60:61], v[60:61], 0.5, v[162:163] op_sel_hi:[1,0,1]
	v_pk_fma_f32 v[58:59], v[58:59], 0.5, v[172:173] op_sel_hi:[1,0,1]
	v_pk_fma_f32 v[56:57], v[56:57], 0.5, v[170:171] op_sel_hi:[1,0,1]
	v_pk_fma_f32 v[54:55], v[54:55], 0.5, v[174:175] op_sel_hi:[1,0,1]
	v_pk_fma_f32 v[52:53], v[52:53], 0.5, v[178:179] op_sel_hi:[1,0,1]
	v_pk_fma_f32 v[50:51], v[50:51], 0.5, v[176:177] op_sel_hi:[1,0,1]
	v_pk_fma_f32 v[48:49], v[48:49], 0.5, v[180:181] op_sel_hi:[1,0,1]
	v_mul_f32_e32 v162, v61, v61
	v_mul_f32_e32 v163, v63, v63
	v_mul_f32_e32 v166, v57, v57
	v_mul_f32_e32 v167, v59, v59
	v_mul_f32_e32 v170, v53, v53
	v_mul_f32_e32 v171, v55, v55
	v_mul_f32_e32 v172, v49, v49
	v_mul_f32_e32 v173, v51, v51
	v_fmac_f32_e32 v162, v60, v60
	v_fmac_f32_e32 v163, v62, v62
	v_fmac_f32_e32 v166, v56, v56
	v_fmac_f32_e32 v167, v58, v58
	v_fmac_f32_e32 v170, v52, v52
	v_fmac_f32_e32 v171, v54, v54
	v_fmac_f32_e32 v172, v48, v48
	v_fmac_f32_e32 v173, v50, v50
	v_add_f32_e32 v162, v162, v163
	v_add_f32_e32 v163, v166, v167
	v_add_f32_e32 v166, v170, v171
	v_add_f32_e32 v167, v172, v173
	v_add_f32_e32 v162, v162, v163
	v_add_f32_e32 v163, v166, v167
	v_add_f32_e32 v162, v162, v163
	ds_bpermute_b32 v163, v205, v162
	s_waitcnt lgkmcnt(0)
	v_add_f32_e32 v162, v162, v163
	ds_bpermute_b32 v163, v206, v162
	s_and_saveexec_b64 s[34:35], s[0:1]
	s_cbranch_execz .LBB0_969
	s_waitcnt lgkmcnt(0)
	v_add_f32_e32 v166, v162, v163
	v_lshl_add_u64 v[162:163], s[48:49], 0, v[186:187]
	v_lshl_add_u64 v[162:163], s[30:31], 2, v[162:163]
	s_lshl_b32 s36, s53, 2
	s_mov_b32 s37, s21
	v_lshl_add_u64 v[162:163], v[162:163], 0, s[36:37]
	v_or_b32_e32 v166, 0x80000000, v166
	global_store_dword v[162:163], v166, off sc1
.LBB0_969:
	s_or_b64 exec, exec, s[34:35]
	v_add_u32_e32 v162, 0x90, v146
	s_waitcnt lgkmcnt(0)
	v_ashrrev_i32_e32 v163, 31, v162
	v_lshlrev_b64 v[166:167], 11, v[162:163]
	v_lshl_add_u64 v[166:167], s[44:45], 0, v[166:167]
	v_lshl_add_u64 v[166:167], v[148:149], 1, v[166:167]
	v_lshlrev_b64 v[190:191], 6, v[162:163]
	s_waitcnt vmcnt(8)
	v_lshlrev_b32_e32 v166, 16, v222
	v_and_b32_e32 v167, 0xffff0000, v222
	v_lshlrev_b32_e32 v170, 16, v223
	v_and_b32_e32 v171, 0xffff0000, v223
	v_lshlrev_b32_e32 v178, 16, v224
	v_and_b32_e32 v179, 0xffff0000, v224
	v_lshlrev_b32_e32 v172, 16, v225
	v_and_b32_e32 v173, 0xffff0000, v225
	v_lshlrev_b32_e32 v180, 16, v226
	v_and_b32_e32 v181, 0xffff0000, v226
	v_lshlrev_b32_e32 v174, 16, v227
	v_and_b32_e32 v175, 0xffff0000, v227
	v_lshlrev_b32_e32 v182, 16, v228
	v_and_b32_e32 v183, 0xffff0000, v228
	v_lshlrev_b32_e32 v176, 16, v229
	v_and_b32_e32 v177, 0xffff0000, v229
	v_pk_fma_f32 v[46:47], v[46:47], 0.5, v[170:171] op_sel_hi:[1,0,1]
	v_pk_fma_f32 v[44:45], v[44:45], 0.5, v[166:167] op_sel_hi:[1,0,1]
	v_pk_fma_f32 v[42:43], v[42:43], 0.5, v[172:173] op_sel_hi:[1,0,1]
	v_pk_fma_f32 v[40:41], v[40:41], 0.5, v[178:179] op_sel_hi:[1,0,1]
	v_pk_fma_f32 v[38:39], v[38:39], 0.5, v[174:175] op_sel_hi:[1,0,1]
	v_pk_fma_f32 v[36:37], v[36:37], 0.5, v[180:181] op_sel_hi:[1,0,1]
	v_pk_fma_f32 v[34:35], v[34:35], 0.5, v[176:177] op_sel_hi:[1,0,1]
	v_pk_fma_f32 v[32:33], v[32:33], 0.5, v[182:183] op_sel_hi:[1,0,1]
	v_mul_f32_e32 v166, v45, v45
	v_mul_f32_e32 v167, v47, v47
	v_mul_f32_e32 v170, v41, v41
	v_mul_f32_e32 v171, v43, v43
	v_mul_f32_e32 v172, v37, v37
	v_mul_f32_e32 v173, v39, v39
	v_mul_f32_e32 v174, v33, v33
	v_mul_f32_e32 v175, v35, v35
	v_fmac_f32_e32 v166, v44, v44
	v_fmac_f32_e32 v167, v46, v46
	v_fmac_f32_e32 v170, v40, v40
	v_fmac_f32_e32 v171, v42, v42
	v_fmac_f32_e32 v172, v36, v36
	v_fmac_f32_e32 v173, v38, v38
	v_fmac_f32_e32 v174, v32, v32
	v_fmac_f32_e32 v175, v34, v34
	v_add_f32_e32 v166, v166, v167
	v_add_f32_e32 v167, v170, v171
	v_add_f32_e32 v170, v172, v173
	v_add_f32_e32 v171, v174, v175
	v_add_f32_e32 v166, v166, v167
	v_add_f32_e32 v167, v170, v171
	v_add_f32_e32 v166, v166, v167
	ds_bpermute_b32 v167, v205, v166
	s_waitcnt lgkmcnt(0)
	v_add_f32_e32 v166, v166, v167
	ds_bpermute_b32 v167, v206, v166
	s_and_saveexec_b64 s[34:35], s[0:1]
	s_cbranch_execz .LBB0_971
	s_waitcnt lgkmcnt(0)
	v_add_f32_e32 v170, v166, v167
	v_lshl_add_u64 v[166:167], s[48:49], 0, v[190:191]
	v_lshl_add_u64 v[166:167], s[30:31], 2, v[166:167]
	s_lshl_b32 s36, s53, 2
	s_mov_b32 s37, s21
	v_lshl_add_u64 v[166:167], v[166:167], 0, s[36:37]
	v_or_b32_e32 v170, 0x80000000, v170
	global_store_dword v[166:167], v170, off sc1
;     __device__ __forceinline__ void operator()(const f32x4 (&acc_)[2][2][4][2], const pg8::Unit& u, int wr, int wc, int fr, int fq) const {
;     ...
;                 const int row = row0 + ai * 128 + m * 16; float ss = 0.f;
; #pragma unroll
;                 for (int bj = 0; bj < 2; ++bj) {
;                     const size_t off = (size_t)row * D + col0 + bj * 128;
;                     const u32x4 r = *(const u32x4*)(resb + off);
;                     const f32x4 x0 = (f32x4){__builtin_bit_cast(float, r.x << 16), __builtin_bit_cast(float, r.x & 0xffff0000u), __builtin_bit_cast(float, r.y << 16), __builtin_bit_cast(float, r.y & 0xffff0000u)};
;                     const f32x4 x1 = (f32x4){__builtin_bit_cast(float, r.z << 16), __builtin_bit_cast(float, r.z & 0xffff0000u), __builtin_bit_cast(float, r.w << 16), __builtin_bit_cast(float, r.w & 0xffff0000u)};
;                     const f32x4 v0 = x0 + A[ai][bj][m][0] * 0.5f, v1 = x1 + A[ai][bj][m][1] * 0.5f;
;                     A[ai][bj][m][0] = v0; A[ai][bj][m][1] = v1;
;                     ss += ((v0[0] * v0[0] + v0[1] * v0[1]) + (v0[2] * v0[2] + v0[3] * v0[3])) + ((v1[0] * v1[0] + v1[1] * v1[1]) + (v1[2] * v1[2] + v1[3] * v1[3]));
;                 }
;                 ss += __shfl_xor(ss, 16); ss += __shfl_xor(ss, 32);
;                 if (fq == 0) __hip_atomic_store(xch + (size_t)row * 16 + u.pn * 4 + wc, ss, __ATOMIC_RELAXED, __HIP_MEMORY_SCOPE_AGENT);
;             }
;         asm volatile("s_waitcnt vmcnt(0)" ::: "memory");
;         unsigned* cw = cnt + 64 * u.pm;
;         if (lane == 0) __hip_atomic_fetch_add(cw, 1u, __ATOMIC_RELAXED, __HIP_MEMORY_SCOPE_AGENT);
.LBB0_971:
	s_or_b64 exec, exec, s[34:35]
	v_add_u32_e32 v166, 0xa0, v146
	s_waitcnt lgkmcnt(0)
	v_ashrrev_i32_e32 v167, 31, v166
	v_lshlrev_b64 v[170:171], 11, v[166:167]
	v_lshl_add_u64 v[170:171], s[44:45], 0, v[170:171]
	v_lshl_add_u64 v[174:175], v[148:149], 1, v[170:171]
	v_lshlrev_b64 v[192:193], 6, v[166:167]
	s_waitcnt vmcnt(6)
	v_lshlrev_b32_e32 v178, 16, v230
	v_and_b32_e32 v179, 0xffff0000, v230
	v_lshlrev_b32_e32 v170, 16, v231
	v_and_b32_e32 v171, 0xffff0000, v231
	v_lshlrev_b32_e32 v180, 16, v232
	v_and_b32_e32 v181, 0xffff0000, v232
	v_lshlrev_b32_e32 v172, 16, v233
	v_and_b32_e32 v173, 0xffff0000, v233
	v_lshlrev_b32_e32 v182, 16, v234
	v_and_b32_e32 v183, 0xffff0000, v234
	v_lshlrev_b32_e32 v174, 16, v235
	v_and_b32_e32 v175, 0xffff0000, v235
	v_lshlrev_b32_e32 v184, 16, v236
	v_and_b32_e32 v185, 0xffff0000, v236
	v_lshlrev_b32_e32 v176, 16, v237
	v_and_b32_e32 v177, 0xffff0000, v237
	v_pk_fma_f32 v[30:31], v[30:31], 0.5, v[170:171] op_sel_hi:[1,0,1]
	v_pk_fma_f32 v[28:29], v[28:29], 0.5, v[178:179] op_sel_hi:[1,0,1]
	v_pk_fma_f32 v[26:27], v[26:27], 0.5, v[172:173] op_sel_hi:[1,0,1]
	v_pk_fma_f32 v[24:25], v[24:25], 0.5, v[180:181] op_sel_hi:[1,0,1]
	v_pk_fma_f32 v[22:23], v[22:23], 0.5, v[174:175] op_sel_hi:[1,0,1]
	v_pk_fma_f32 v[20:21], v[20:21], 0.5, v[182:183] op_sel_hi:[1,0,1]
	v_pk_fma_f32 v[18:19], v[18:19], 0.5, v[176:177] op_sel_hi:[1,0,1]
	v_pk_fma_f32 v[16:17], v[16:17], 0.5, v[184:185] op_sel_hi:[1,0,1]
	v_mul_f32_e32 v170, v29, v29
	v_mul_f32_e32 v171, v31, v31
	v_mul_f32_e32 v172, v25, v25
	v_mul_f32_e32 v173, v27, v27
	v_mul_f32_e32 v174, v21, v21
	v_mul_f32_e32 v175, v23, v23
	v_mul_f32_e32 v176, v17, v17
	v_mul_f32_e32 v177, v19, v19
	v_fmac_f32_e32 v170, v28, v28
	v_fmac_f32_e32 v171, v30, v30
	v_fmac_f32_e32 v172, v24, v24
	v_fmac_f32_e32 v173, v26, v26
	v_fmac_f32_e32 v174, v20, v20
	v_fmac_f32_e32 v175, v22, v22
	v_fmac_f32_e32 v176, v16, v16
	v_fmac_f32_e32 v177, v18, v18
	v_add_f32_e32 v170, v170, v171
	v_add_f32_e32 v171, v172, v173
	v_add_f32_e32 v172, v174, v175
	v_add_f32_e32 v173, v176, v177
	v_add_f32_e32 v170, v170, v171
	v_add_f32_e32 v171, v172, v173
	v_add_f32_e32 v170, v170, v171
	ds_bpermute_b32 v171, v205, v170
	s_waitcnt lgkmcnt(0)
	v_add_f32_e32 v170, v170, v171
	ds_bpermute_b32 v171, v206, v170
	s_and_saveexec_b64 s[34:35], s[0:1]
	s_cbranch_execz .LBB0_973
	s_waitcnt lgkmcnt(0)
	v_add_f32_e32 v172, v170, v171
	v_lshl_add_u64 v[170:171], s[48:49], 0, v[192:193]
	v_lshl_add_u64 v[170:171], s[30:31], 2, v[170:171]
	s_lshl_b32 s36, s53, 2
	s_mov_b32 s37, s21
	v_lshl_add_u64 v[170:171], v[170:171], 0, s[36:37]
	v_or_b32_e32 v172, 0x80000000, v172
	global_store_dword v[170:171], v172, off sc1
.LBB0_973:
	s_or_b64 exec, exec, s[34:35]
	v_add_u32_e32 v170, 0xb0, v146
	s_waitcnt lgkmcnt(0)
	v_ashrrev_i32_e32 v171, 31, v170
	v_lshlrev_b64 v[172:173], 11, v[170:171]
	v_lshl_add_u64 v[172:173], s[44:45], 0, v[172:173]
	v_lshl_add_u64 v[176:177], v[148:149], 1, v[172:173]
	s_waitcnt vmcnt(4)
	v_lshlrev_b32_e32 v180, 16, v238
	v_and_b32_e32 v181, 0xffff0000, v238
	v_lshlrev_b32_e32 v172, 16, v239
	v_and_b32_e32 v173, 0xffff0000, v239
	v_lshlrev_b32_e32 v182, 16, v240
	v_and_b32_e32 v183, 0xffff0000, v240
	v_lshlrev_b32_e32 v184, 16, v241
	v_and_b32_e32 v185, 0xffff0000, v241
	v_lshlrev_b32_e32 v188, 16, v242
	v_and_b32_e32 v189, 0xffff0000, v242
	v_lshlrev_b32_e32 v194, 16, v243
	v_and_b32_e32 v195, 0xffff0000, v243
	v_lshlrev_b32_e32 v208, 16, v244
	v_and_b32_e32 v209, 0xffff0000, v244
	v_lshlrev_b32_e32 v210, 16, v245
	v_and_b32_e32 v211, 0xffff0000, v245
	v_pk_fma_f32 v[174:175], v[14:15], 0.5, v[172:173] op_sel_hi:[1,0,1]
	v_pk_fma_f32 v[178:179], v[12:13], 0.5, v[180:181] op_sel_hi:[1,0,1]
	v_pk_fma_f32 v[172:173], v[10:11], 0.5, v[184:185] op_sel_hi:[1,0,1]
	v_pk_fma_f32 v[176:177], v[8:9], 0.5, v[182:183] op_sel_hi:[1,0,1]
	v_pk_fma_f32 v[180:181], v[6:7], 0.5, v[194:195] op_sel_hi:[1,0,1]
	v_pk_fma_f32 v[182:183], v[4:5], 0.5, v[188:189] op_sel_hi:[1,0,1]
	v_pk_fma_f32 v[184:185], v[2:3], 0.5, v[210:211] op_sel_hi:[1,0,1]
	v_pk_fma_f32 v[188:189], v[0:1], 0.5, v[208:209] op_sel_hi:[1,0,1]
	v_mul_f32_e32 v0, v179, v179
	v_mul_f32_e32 v1, v175, v175
	v_mul_f32_e32 v2, v177, v177
	v_mul_f32_e32 v3, v173, v173
	v_mul_f32_e32 v4, v183, v183
	v_mul_f32_e32 v5, v181, v181
	v_mul_f32_e32 v6, v189, v189
	v_mul_f32_e32 v7, v185, v185
	v_fmac_f32_e32 v0, v178, v178
	v_fmac_f32_e32 v1, v174, v174
	v_fmac_f32_e32 v2, v176, v176
	v_fmac_f32_e32 v3, v172, v172
	v_fmac_f32_e32 v4, v182, v182
	v_fmac_f32_e32 v5, v180, v180
	v_fmac_f32_e32 v6, v188, v188
	v_fmac_f32_e32 v7, v184, v184
	v_add_f32_e32 v0, v0, v1
	v_add_f32_e32 v1, v2, v3
	v_add_f32_e32 v2, v4, v5
	v_add_f32_e32 v3, v6, v7
	v_add_f32_e32 v0, v0, v1
	v_add_f32_e32 v1, v2, v3
	v_add_f32_e32 v0, v0, v1
	ds_bpermute_b32 v1, v205, v0
	v_lshlrev_b64 v[194:195], 6, v[170:171]
	s_waitcnt lgkmcnt(0)
	v_add_f32_e32 v0, v0, v1
	ds_bpermute_b32 v1, v206, v0
	s_and_saveexec_b64 s[34:35], s[0:1]
	s_cbranch_execz .LBB0_975
	s_waitcnt lgkmcnt(0)
	v_add_f32_e32 v2, v0, v1
	v_lshl_add_u64 v[0:1], s[48:49], 0, v[194:195]
	v_lshl_add_u64 v[0:1], s[30:31], 2, v[0:1]
	s_lshl_b32 s30, s53, 2
	s_mov_b32 s31, s21
	v_lshl_add_u64 v[0:1], v[0:1], 0, s[30:31]
	v_or_b32_e32 v2, 0x80000000, v2
	global_store_dword v[0:1], v2, off sc1
.LBB0_975:
	s_or_b64 exec, exec, s[34:35]
	s_waitcnt lgkmcnt(0)
;     __device__ __forceinline__ void operator()(const f32x4 (&acc_)[2][2][4][2], const pg8::Unit& u, int wr, int wc, int fr, int fq) const {
;     ...
;         { unsigned spins = 0;
;           while ((unsigned)__builtin_amdgcn_readfirstlane(__hip_atomic_load(cw, __ATOMIC_RELAXED, __HIP_MEMORY_SCOPE_AGENT)) < 32u) { if (++spins > (1u << 22)) break; __builtin_amdgcn_s_sleep(2); } }
;         __builtin_amdgcn_fence(__ATOMIC_ACQUIRE, "agent");
;         asm volatile("s_waitcnt vmcnt(0)" ::: "memory");
;         f32x4 g[2][2];
; #pragma unroll
;         for (int bj = 0; bj < 2; ++bj) { g[bj][0] = *(const f32x4*)(gain + col0 + bj * 128); g[bj][1] = *(const f32x4*)(gain + col0 + bj * 128 + 4); }
; #pragma unroll
;         for (int ai = 0; ai < 2; ++ai)
; #pragma unroll
;             for (int m = 0; m < 4; ++m) {
;                 const int row = row0 + ai * 128 + m * 16; const float* xp = xch + (size_t)row * 16 + 4 * fq;
;                 float s = (__hip_atomic_load(xp + 0, __ATOMIC_RELAXED, __HIP_MEMORY_SCOPE_AGENT) + __hip_atomic_load(xp + 1, __ATOMIC_RELAXED, __HIP_MEMORY_SCOPE_AGENT))
;                         + (__hip_atomic_load(xp + 2, __ATOMIC_RELAXED, __HIP_MEMORY_SCOPE_AGENT) + __hip_atomic_load(xp + 3, __ATOMIC_RELAXED, __HIP_MEMORY_SCOPE_AGENT));
;                 s += __shfl_xor(s, 16); s += __shfl_xor(s, 32);
;                 const float rstd = __builtin_amdgcn_rsqf(s * (1.0f / 1024.0f) + EPS);
; #pragma unroll
;                 for (int bj = 0; bj < 2; ++bj) { const size_t off = (size_t)row * D + col0 + bj * 128;
;                     *(f32x4*)(out + off) = A[ai][bj][m][0] * rstd * g[bj][0]; *(f32x4*)(out + off + 4) = A[ai][bj][m][1] * rstd * g[bj][1]; }
.LBB0_982:
	v_lshlrev_b64 v[148:149], 2, v[148:149]
	v_lshl_add_u64 v[8:9], s[24:25], 0, v[148:149]
	v_lshl_add_u64 v[156:157], v[136:137], 0, v[156:157]
	global_load_dwordx4 v[4:7], v[8:9], off offset:16
	global_load_dwordx4 v[12:15], v[8:9], off
	global_load_dwordx4 v[0:3], v[8:9], off offset:528
	s_nop 0
	global_load_dwordx4 v[8:11], v[8:9], off offset:512
	s_nop 0
	v_lshlrev_b64 v[146:147], 12, v[146:147]
	v_lshl_add_u64 v[146:147], s[8:9], 0, v[146:147]
	v_lshl_add_u64 v[146:147], v[146:147], 0, v[148:149]
	v_lshl_add_u64 v[160:161], v[136:137], 0, v[160:161]
	v_lshl_add_u64 v[242:243], v[136:137], 0, v[164:165]
	v_lshl_add_u64 v[244:245], v[136:137], 0, v[168:169]
	v_lshl_add_u64 v[248:249], v[136:137], 0, v[186:187]
	v_lshl_add_u64 v[250:251], v[136:137], 0, v[190:191]
	v_lshl_add_u64 v[252:253], v[136:137], 0, v[192:193]
	v_lshl_add_u64 v[254:255], v[136:137], 0, v[194:195]
	s_and_b64 vcc, exec, s[4:5]
	s_mov_b64 s[4:5], -1
	s_movk_i32 s36, 0x400
	s_mov_b64 s[30:31], exec
	s_mov_b32 exec_lo, 0x10001
	s_mov_b32 exec_hi, 0x10001
.Lg9_poll7:
	global_load_dwordx4 v[238:241], v[254:255], off sc1
	s_waitcnt vmcnt(0)
	v_and_b32_e32 v212, v238, v239
	v_and_b32_e32 v213, v240, v241
	v_and_b32_e32 v212, v212, v213
	v_cmp_gt_i32_e64 s[34:35], 0, v212
	s_add_i32 s36, s36, -1
	s_cmp_le_i32 s36, 0
	s_cbranch_scc1 .Lg9_all
	s_xor_b64 s[34:35], s[34:35], exec
	s_cbranch_scc0 .Lg9_all
	s_sleep 2
	s_branch .Lg9_poll7
.Lg9_all:
	s_mov_b64 exec, s[30:31]
	global_load_dwordx4 v[208:211], v[156:157], off sc1
	global_load_dwordx4 v[214:217], v[160:161], off sc1
	global_load_dwordx4 v[218:221], v[242:243], off sc1
	global_load_dwordx4 v[222:225], v[244:245], off sc1
	global_load_dwordx4 v[226:229], v[248:249], off sc1
	global_load_dwordx4 v[230:233], v[250:251], off sc1
	global_load_dwordx4 v[234:237], v[252:253], off sc1
	global_load_dwordx4 v[238:241], v[254:255], off sc1
	s_waitcnt vmcnt(0)
	v_and_b32_e32 v212, v208, v209
	v_and_b32_e32 v213, v210, v211
	v_and_b32_e32 v212, v212, v214
	v_and_b32_e32 v213, v213, v215
	v_and_b32_e32 v212, v212, v216
	v_and_b32_e32 v213, v213, v217
	v_and_b32_e32 v212, v212, v218
	v_and_b32_e32 v213, v213, v219
	v_and_b32_e32 v212, v212, v220
	v_and_b32_e32 v213, v213, v221
	v_and_b32_e32 v212, v212, v222
	v_and_b32_e32 v213, v213, v223
	v_and_b32_e32 v212, v212, v224
	v_and_b32_e32 v213, v213, v225
	v_and_b32_e32 v212, v212, v226
	v_and_b32_e32 v213, v213, v227
	v_and_b32_e32 v212, v212, v228
	v_and_b32_e32 v213, v213, v229
	v_and_b32_e32 v212, v212, v230
	v_and_b32_e32 v213, v213, v231
	v_and_b32_e32 v212, v212, v232
	v_and_b32_e32 v213, v213, v233
	v_and_b32_e32 v212, v212, v234
	v_and_b32_e32 v213, v213, v235
	v_and_b32_e32 v212, v212, v236
	v_and_b32_e32 v213, v213, v237
	v_and_b32_e32 v212, v212, v238
	v_and_b32_e32 v213, v213, v239
	v_and_b32_e32 v212, v212, v240
	v_and_b32_e32 v213, v213, v241
	v_and_b32_e32 v212, v212, v213
	v_cmp_gt_i32_e64 s[34:35], 0, v212
	s_add_i32 s36, s36, -1
	s_cmp_le_i32 s36, 0
	s_cbranch_scc1 .Lg9_go
	s_xor_b64 s[34:35], s[34:35], exec
	s_cbranch_scc0 .Lg9_go
	s_sleep 2
	s_branch .Lg9_all
.Lg9_go:
	v_add_f32_e64 v156, |v208|, |v209|
	v_add_f32_e64 v157, |v210|, |v211|
	s_nop 0
	v_add_f32_e32 v156, v156, v157
	ds_bpermute_b32 v157, v205, v156
	s_waitcnt lgkmcnt(0)
	v_add_f32_e32 v156, v156, v157
	ds_bpermute_b32 v157, v206, v156
	s_waitcnt lgkmcnt(0)
	v_add_f32_e32 v156, v156, v157
	v_fmamk_f32 v156, v156, 0x3a800000, v204
	v_rsq_f32_e32 v156, v156
	s_nop 0
	v_pk_mul_f32 v[124:125], v[124:125], v[156:157] op_sel_hi:[1,0]
	v_pk_mul_f32 v[126:127], v[126:127], v[156:157] op_sel_hi:[1,0]
	v_pk_mul_f32 v[120:121], v[120:121], v[156:157] op_sel_hi:[1,0]
	v_pk_mul_f32 v[122:123], v[122:123], v[156:157] op_sel_hi:[1,0]
	v_pk_mul_f32 v[208:209], v[116:117], v[156:157] op_sel_hi:[1,0]
	v_pk_mul_f32 v[210:211], v[118:119], v[156:157] op_sel_hi:[1,0]
	v_pk_mul_f32 v[212:213], v[112:113], v[156:157] op_sel_hi:[1,0]
	v_pk_mul_f32 v[156:157], v[114:115], v[156:157] op_sel_hi:[1,0]
	v_pk_mul_f32 v[114:115], v[14:15], v[126:127]
	v_pk_mul_f32 v[112:113], v[12:13], v[124:125]
	v_pk_mul_f32 v[118:119], v[6:7], v[122:123]
	v_pk_mul_f32 v[116:117], v[4:5], v[120:121]
	v_pk_mul_f32 v[122:123], v[10:11], v[210:211]
	v_pk_mul_f32 v[120:121], v[8:9], v[208:209]
	v_pk_mul_f32 v[126:127], v[2:3], v[156:157]
	v_pk_mul_f32 v[124:125], v[0:1], v[212:213]
	global_store_dwordx4 v[146:147], v[112:115], off nt
	global_store_dwordx4 v[146:147], v[116:119], off offset:16 nt
	global_store_dwordx4 v[146:147], v[120:123], off offset:512 nt
	global_store_dwordx4 v[146:147], v[124:127], off offset:528 nt
	v_add_f32_e64 v112, |v214|, |v215|
	v_add_f32_e64 v113, |v216|, |v217|
	s_nop 0
	v_add_f32_e32 v112, v112, v113
	ds_bpermute_b32 v113, v205, v112
	s_waitcnt lgkmcnt(0)
	v_add_f32_e32 v114, v112, v113
	ds_bpermute_b32 v115, v206, v114
	v_lshlrev_b64 v[112:113], 12, v[150:151]
	v_lshl_add_u64 v[112:113], s[8:9], 0, v[112:113]
	v_lshl_add_u64 v[112:113], v[112:113], 0, v[148:149]
	s_waitcnt lgkmcnt(0)
;     __device__ __forceinline__ void operator()(const f32x4 (&acc_)[2][2][4][2], const pg8::Unit& u, int wr, int wc, int fr, int fq) const {
;     ...
;         for (int ai = 0; ai < 2; ++ai)
; #pragma unroll
;             for (int m = 0; m < 4; ++m) {
;                 const int row = row0 + ai * 128 + m * 16; const float* xp = xch + (size_t)row * 16 + 4 * fq;
;                 float s = (__hip_atomic_load(xp + 0, __ATOMIC_RELAXED, __HIP_MEMORY_SCOPE_AGENT) + __hip_atomic_load(xp + 1, __ATOMIC_RELAXED, __HIP_MEMORY_SCOPE_AGENT))
;                         + (__hip_atomic_load(xp + 2, __ATOMIC_RELAXED, __HIP_MEMORY_SCOPE_AGENT) + __hip_atomic_load(xp + 3, __ATOMIC_RELAXED, __HIP_MEMORY_SCOPE_AGENT));
;                 s += __shfl_xor(s, 16); s += __shfl_xor(s, 32);
;                 const float rstd = __builtin_amdgcn_rsqf(s * (1.0f / 1024.0f) + EPS);
; #pragma unroll
;                 for (int bj = 0; bj < 2; ++bj) { const size_t off = (size_t)row * D + col0 + bj * 128;
;                     *(f32x4*)(out + off) = A[ai][bj][m][0] * rstd * g[bj][0]; *(f32x4*)(out + off + 4) = A[ai][bj][m][1] * rstd * g[bj][1]; }
	v_add_f32_e32 v114, v114, v115
	v_fmamk_f32 v114, v114, 0x3a800000, v204
	v_rsq_f32_e32 v114, v114
	s_nop 0
	v_pk_mul_f32 v[108:109], v[108:109], v[114:115] op_sel_hi:[1,0]
	v_pk_mul_f32 v[110:111], v[110:111], v[114:115] op_sel_hi:[1,0]
	v_pk_mul_f32 v[104:105], v[104:105], v[114:115] op_sel_hi:[1,0]
	v_pk_mul_f32 v[106:107], v[106:107], v[114:115] op_sel_hi:[1,0]
	v_pk_mul_f32 v[118:119], v[100:101], v[114:115] op_sel_hi:[1,0]
	v_pk_mul_f32 v[120:121], v[102:103], v[114:115] op_sel_hi:[1,0]
	v_pk_mul_f32 v[122:123], v[96:97], v[114:115] op_sel_hi:[1,0]
	v_pk_mul_f32 v[114:115], v[98:99], v[114:115] op_sel_hi:[1,0]
	v_pk_mul_f32 v[98:99], v[14:15], v[110:111]
	v_pk_mul_f32 v[96:97], v[12:13], v[108:109]
	v_pk_mul_f32 v[102:103], v[6:7], v[106:107]
	v_pk_mul_f32 v[100:101], v[4:5], v[104:105]
	v_pk_mul_f32 v[106:107], v[10:11], v[120:121]
	v_pk_mul_f32 v[104:105], v[8:9], v[118:119]
	v_pk_mul_f32 v[110:111], v[2:3], v[114:115]
	v_pk_mul_f32 v[108:109], v[0:1], v[122:123]
	global_store_dwordx4 v[112:113], v[96:99], off nt
	global_store_dwordx4 v[112:113], v[100:103], off offset:16 nt
	global_store_dwordx4 v[112:113], v[104:107], off offset:512 nt
	global_store_dwordx4 v[112:113], v[108:111], off offset:528 nt
	v_add_f32_e64 v96, |v218|, |v219|
	v_add_f32_e64 v97, |v220|, |v221|
	s_nop 0
	v_add_f32_e32 v96, v96, v97
	ds_bpermute_b32 v97, v205, v96
	s_waitcnt lgkmcnt(0)
	v_add_f32_e32 v98, v96, v97
	ds_bpermute_b32 v99, v206, v98
	v_lshlrev_b64 v[96:97], 12, v[152:153]
	v_lshl_add_u64 v[96:97], s[8:9], 0, v[96:97]
	v_lshl_add_u64 v[96:97], v[96:97], 0, v[148:149]
	s_waitcnt lgkmcnt(0)
	v_add_f32_e32 v98, v98, v99
	v_fmamk_f32 v98, v98, 0x3a800000, v204
	v_rsq_f32_e32 v98, v98
	s_nop 0
	v_pk_mul_f32 v[92:93], v[92:93], v[98:99] op_sel_hi:[1,0]
	v_pk_mul_f32 v[94:95], v[94:95], v[98:99] op_sel_hi:[1,0]
	v_pk_mul_f32 v[88:89], v[88:89], v[98:99] op_sel_hi:[1,0]
	v_pk_mul_f32 v[90:91], v[90:91], v[98:99] op_sel_hi:[1,0]
	v_pk_mul_f32 v[102:103], v[84:85], v[98:99] op_sel_hi:[1,0]
	v_pk_mul_f32 v[104:105], v[86:87], v[98:99] op_sel_hi:[1,0]
	v_pk_mul_f32 v[106:107], v[80:81], v[98:99] op_sel_hi:[1,0]
	v_pk_mul_f32 v[98:99], v[82:83], v[98:99] op_sel_hi:[1,0]
	v_pk_mul_f32 v[82:83], v[14:15], v[94:95]
	v_pk_mul_f32 v[80:81], v[12:13], v[92:93]
	v_pk_mul_f32 v[86:87], v[6:7], v[90:91]
	v_pk_mul_f32 v[84:85], v[4:5], v[88:89]
	v_pk_mul_f32 v[90:91], v[10:11], v[104:105]
	v_pk_mul_f32 v[88:89], v[8:9], v[102:103]
	v_pk_mul_f32 v[94:95], v[2:3], v[98:99]
	v_pk_mul_f32 v[92:93], v[0:1], v[106:107]
	global_store_dwordx4 v[96:97], v[80:83], off nt
	global_store_dwordx4 v[96:97], v[84:87], off offset:16 nt
	global_store_dwordx4 v[96:97], v[88:91], off offset:512 nt
	global_store_dwordx4 v[96:97], v[92:95], off offset:528 nt
	v_add_f32_e64 v80, |v222|, |v223|
	v_add_f32_e64 v81, |v224|, |v225|
	s_nop 0
	v_add_f32_e32 v80, v80, v81
	ds_bpermute_b32 v81, v205, v80
	s_waitcnt lgkmcnt(0)
	v_add_f32_e32 v82, v80, v81
	ds_bpermute_b32 v83, v206, v82
	v_lshlrev_b64 v[80:81], 12, v[154:155]
	v_lshl_add_u64 v[80:81], s[8:9], 0, v[80:81]
	v_lshl_add_u64 v[80:81], v[80:81], 0, v[148:149]
	s_waitcnt lgkmcnt(0)
	v_add_f32_e32 v82, v82, v83
	v_fmamk_f32 v82, v82, 0x3a800000, v204
	v_rsq_f32_e32 v82, v82
	s_nop 0
	v_pk_mul_f32 v[76:77], v[76:77], v[82:83] op_sel_hi:[1,0]
	v_pk_mul_f32 v[78:79], v[78:79], v[82:83] op_sel_hi:[1,0]
	v_pk_mul_f32 v[72:73], v[72:73], v[82:83] op_sel_hi:[1,0]
	v_pk_mul_f32 v[74:75], v[74:75], v[82:83] op_sel_hi:[1,0]
	v_pk_mul_f32 v[86:87], v[68:69], v[82:83] op_sel_hi:[1,0]
	v_pk_mul_f32 v[88:89], v[70:71], v[82:83] op_sel_hi:[1,0]
	v_pk_mul_f32 v[90:91], v[64:65], v[82:83] op_sel_hi:[1,0]
	v_pk_mul_f32 v[82:83], v[66:67], v[82:83] op_sel_hi:[1,0]
	v_pk_mul_f32 v[66:67], v[14:15], v[78:79]
	v_pk_mul_f32 v[64:65], v[12:13], v[76:77]
	v_pk_mul_f32 v[70:71], v[6:7], v[74:75]
	v_pk_mul_f32 v[68:69], v[4:5], v[72:73]
	v_pk_mul_f32 v[74:75], v[10:11], v[88:89]
	v_pk_mul_f32 v[72:73], v[8:9], v[86:87]
	v_pk_mul_f32 v[78:79], v[2:3], v[82:83]
	v_pk_mul_f32 v[76:77], v[0:1], v[90:91]
	global_store_dwordx4 v[80:81], v[64:67], off nt
	global_store_dwordx4 v[80:81], v[68:71], off offset:16 nt
	global_store_dwordx4 v[80:81], v[72:75], off offset:512 nt
	global_store_dwordx4 v[80:81], v[76:79], off offset:528 nt
	v_add_f32_e64 v64, |v226|, |v227|
	v_add_f32_e64 v65, |v228|, |v229|
	s_nop 0
	v_add_f32_e32 v64, v64, v65
	ds_bpermute_b32 v65, v205, v64
	s_waitcnt lgkmcnt(0)
	v_add_f32_e32 v66, v64, v65
	ds_bpermute_b32 v67, v206, v66
	v_lshlrev_b64 v[64:65], 12, v[158:159]
	v_lshl_add_u64 v[64:65], s[8:9], 0, v[64:65]
	v_lshl_add_u64 v[64:65], v[64:65], 0, v[148:149]
	s_waitcnt lgkmcnt(0)
;     __device__ __forceinline__ void operator()(const f32x4 (&acc_)[2][2][4][2], const pg8::Unit& u, int wr, int wc, int fr, int fq) const {
;     ...
;         for (int ai = 0; ai < 2; ++ai)
; #pragma unroll
;             for (int m = 0; m < 4; ++m) {
;                 const int row = row0 + ai * 128 + m * 16; const float* xp = xch + (size_t)row * 16 + 4 * fq;
;                 float s = (__hip_atomic_load(xp + 0, __ATOMIC_RELAXED, __HIP_MEMORY_SCOPE_AGENT) + __hip_atomic_load(xp + 1, __ATOMIC_RELAXED, __HIP_MEMORY_SCOPE_AGENT))
;                         + (__hip_atomic_load(xp + 2, __ATOMIC_RELAXED, __HIP_MEMORY_SCOPE_AGENT) + __hip_atomic_load(xp + 3, __ATOMIC_RELAXED, __HIP_MEMORY_SCOPE_AGENT));
;                 s += __shfl_xor(s, 16); s += __shfl_xor(s, 32);
;                 const float rstd = __builtin_amdgcn_rsqf(s * (1.0f / 1024.0f) + EPS);
; #pragma unroll
;                 for (int bj = 0; bj < 2; ++bj) { const size_t off = (size_t)row * D + col0 + bj * 128;
;                     *(f32x4*)(out + off) = A[ai][bj][m][0] * rstd * g[bj][0]; *(f32x4*)(out + off + 4) = A[ai][bj][m][1] * rstd * g[bj][1]; }
	v_add_f32_e32 v66, v66, v67
	v_fmamk_f32 v66, v66, 0x3a800000, v204
	v_rsq_f32_e32 v66, v66
	s_nop 0
	v_pk_mul_f32 v[60:61], v[60:61], v[66:67] op_sel_hi:[1,0]
	v_pk_mul_f32 v[62:63], v[62:63], v[66:67] op_sel_hi:[1,0]
	v_pk_mul_f32 v[56:57], v[56:57], v[66:67] op_sel_hi:[1,0]
	v_pk_mul_f32 v[58:59], v[58:59], v[66:67] op_sel_hi:[1,0]
	v_pk_mul_f32 v[70:71], v[52:53], v[66:67] op_sel_hi:[1,0]
	v_pk_mul_f32 v[72:73], v[54:55], v[66:67] op_sel_hi:[1,0]
	v_pk_mul_f32 v[74:75], v[48:49], v[66:67] op_sel_hi:[1,0]
	v_pk_mul_f32 v[66:67], v[50:51], v[66:67] op_sel_hi:[1,0]
	v_pk_mul_f32 v[50:51], v[14:15], v[62:63]
	v_pk_mul_f32 v[48:49], v[12:13], v[60:61]
	v_pk_mul_f32 v[54:55], v[6:7], v[58:59]
	v_pk_mul_f32 v[52:53], v[4:5], v[56:57]
	v_pk_mul_f32 v[58:59], v[10:11], v[72:73]
	v_pk_mul_f32 v[56:57], v[8:9], v[70:71]
	v_pk_mul_f32 v[62:63], v[2:3], v[66:67]
	v_pk_mul_f32 v[60:61], v[0:1], v[74:75]
	global_store_dwordx4 v[64:65], v[48:51], off nt
	global_store_dwordx4 v[64:65], v[52:55], off offset:16 nt
	global_store_dwordx4 v[64:65], v[56:59], off offset:512 nt
	global_store_dwordx4 v[64:65], v[60:63], off offset:528 nt
	v_add_f32_e64 v48, |v230|, |v231|
	v_add_f32_e64 v49, |v232|, |v233|
	s_nop 0
	v_add_f32_e32 v48, v48, v49
	ds_bpermute_b32 v49, v205, v48
	s_waitcnt lgkmcnt(0)
	v_add_f32_e32 v50, v48, v49
	ds_bpermute_b32 v51, v206, v50
	v_lshlrev_b64 v[48:49], 12, v[162:163]
	v_lshl_add_u64 v[48:49], s[8:9], 0, v[48:49]
	v_lshl_add_u64 v[48:49], v[48:49], 0, v[148:149]
	s_waitcnt lgkmcnt(0)
	v_add_f32_e32 v50, v50, v51
	v_fmamk_f32 v50, v50, 0x3a800000, v204
	v_rsq_f32_e32 v50, v50
	s_nop 0
	v_pk_mul_f32 v[44:45], v[44:45], v[50:51] op_sel_hi:[1,0]
	v_pk_mul_f32 v[46:47], v[46:47], v[50:51] op_sel_hi:[1,0]
	v_pk_mul_f32 v[40:41], v[40:41], v[50:51] op_sel_hi:[1,0]
	v_pk_mul_f32 v[42:43], v[42:43], v[50:51] op_sel_hi:[1,0]
	v_pk_mul_f32 v[54:55], v[36:37], v[50:51] op_sel_hi:[1,0]
	v_pk_mul_f32 v[56:57], v[38:39], v[50:51] op_sel_hi:[1,0]
	v_pk_mul_f32 v[58:59], v[32:33], v[50:51] op_sel_hi:[1,0]
	v_pk_mul_f32 v[50:51], v[34:35], v[50:51] op_sel_hi:[1,0]
	v_pk_mul_f32 v[34:35], v[14:15], v[46:47]
	v_pk_mul_f32 v[32:33], v[12:13], v[44:45]
	v_pk_mul_f32 v[38:39], v[6:7], v[42:43]
	v_pk_mul_f32 v[36:37], v[4:5], v[40:41]
	v_pk_mul_f32 v[42:43], v[10:11], v[56:57]
	v_pk_mul_f32 v[40:41], v[8:9], v[54:55]
	v_pk_mul_f32 v[46:47], v[2:3], v[50:51]
	v_pk_mul_f32 v[44:45], v[0:1], v[58:59]
	global_store_dwordx4 v[48:49], v[32:35], off nt
	global_store_dwordx4 v[48:49], v[36:39], off offset:16 nt
	global_store_dwordx4 v[48:49], v[40:43], off offset:512 nt
	global_store_dwordx4 v[48:49], v[44:47], off offset:528 nt
	v_add_f32_e64 v32, |v234|, |v235|
	v_add_f32_e64 v33, |v236|, |v237|
	s_nop 0
	v_add_f32_e32 v32, v32, v33
	ds_bpermute_b32 v33, v205, v32
	s_waitcnt lgkmcnt(0)
	v_add_f32_e32 v34, v32, v33
	ds_bpermute_b32 v35, v206, v34
	v_lshlrev_b64 v[32:33], 12, v[166:167]
	v_lshl_add_u64 v[32:33], s[8:9], 0, v[32:33]
	v_lshl_add_u64 v[32:33], v[32:33], 0, v[148:149]
	s_waitcnt lgkmcnt(0)
	v_add_f32_e32 v34, v34, v35
	v_fmamk_f32 v34, v34, 0x3a800000, v204
	v_rsq_f32_e32 v34, v34
	s_nop 0
	v_pk_mul_f32 v[28:29], v[28:29], v[34:35] op_sel_hi:[1,0]
	v_pk_mul_f32 v[30:31], v[30:31], v[34:35] op_sel_hi:[1,0]
	v_pk_mul_f32 v[24:25], v[24:25], v[34:35] op_sel_hi:[1,0]
	v_pk_mul_f32 v[26:27], v[26:27], v[34:35] op_sel_hi:[1,0]
	v_pk_mul_f32 v[38:39], v[20:21], v[34:35] op_sel_hi:[1,0]
	v_pk_mul_f32 v[40:41], v[22:23], v[34:35] op_sel_hi:[1,0]
	v_pk_mul_f32 v[42:43], v[16:17], v[34:35] op_sel_hi:[1,0]
	v_pk_mul_f32 v[34:35], v[18:19], v[34:35] op_sel_hi:[1,0]
	v_pk_mul_f32 v[18:19], v[14:15], v[30:31]
	v_pk_mul_f32 v[16:17], v[12:13], v[28:29]
	v_pk_mul_f32 v[22:23], v[6:7], v[26:27]
	v_pk_mul_f32 v[20:21], v[4:5], v[24:25]
	v_pk_mul_f32 v[26:27], v[10:11], v[40:41]
	v_pk_mul_f32 v[24:25], v[8:9], v[38:39]
	v_pk_mul_f32 v[30:31], v[2:3], v[34:35]
	v_pk_mul_f32 v[28:29], v[0:1], v[42:43]
	global_store_dwordx4 v[32:33], v[16:19], off nt
	global_store_dwordx4 v[32:33], v[20:23], off offset:16 nt
	global_store_dwordx4 v[32:33], v[24:27], off offset:512 nt
	global_store_dwordx4 v[32:33], v[28:31], off offset:528 nt
	v_add_f32_e64 v16, |v238|, |v239|
	v_add_f32_e64 v17, |v240|, |v241|
	s_nop 0
	v_add_f32_e32 v16, v16, v17
	ds_bpermute_b32 v17, v205, v16
	s_waitcnt lgkmcnt(0)
	v_add_f32_e32 v18, v16, v17
	ds_bpermute_b32 v19, v206, v18
	v_lshlrev_b64 v[16:17], 12, v[170:171]
	v_lshl_add_u64 v[16:17], s[8:9], 0, v[16:17]
	v_lshl_add_u64 v[16:17], v[16:17], 0, v[148:149]
	s_waitcnt lgkmcnt(0)
	v_add_f32_e32 v18, v18, v19
	v_fmamk_f32 v18, v18, 0x3a800000, v204
	v_rsq_f32_e32 v18, v18
	s_nop 0
	v_pk_mul_f32 v[20:21], v[178:179], v[18:19] op_sel_hi:[1,0]
	v_pk_mul_f32 v[22:23], v[174:175], v[18:19] op_sel_hi:[1,0]
	v_pk_mul_f32 v[24:25], v[176:177], v[18:19] op_sel_hi:[1,0]
	v_pk_mul_f32 v[26:27], v[172:173], v[18:19] op_sel_hi:[1,0]
	v_pk_mul_f32 v[28:29], v[182:183], v[18:19] op_sel_hi:[1,0]
	v_pk_mul_f32 v[30:31], v[180:181], v[18:19] op_sel_hi:[1,0]
	v_pk_mul_f32 v[32:33], v[188:189], v[18:19] op_sel_hi:[1,0]
	v_pk_mul_f32 v[18:19], v[184:185], v[18:19] op_sel_hi:[1,0]
	v_pk_mul_f32 v[14:15], v[14:15], v[22:23]
	v_pk_mul_f32 v[12:13], v[12:13], v[20:21]
	v_pk_mul_f32 v[6:7], v[6:7], v[26:27]
	v_pk_mul_f32 v[4:5], v[4:5], v[24:25]
	v_pk_mul_f32 v[10:11], v[10:11], v[30:31]
	v_pk_mul_f32 v[8:9], v[8:9], v[28:29]
	v_pk_mul_f32 v[2:3], v[2:3], v[18:19]
	v_pk_mul_f32 v[0:1], v[0:1], v[32:33]
	global_store_dwordx4 v[16:17], v[12:15], off nt
	global_store_dwordx4 v[16:17], v[4:7], off offset:16 nt
	global_store_dwordx4 v[16:17], v[8:11], off offset:512 nt
	global_store_dwordx4 v[16:17], v[0:3], off offset:528 nt
	s_cbranch_vccnz .LBB0_948
	s_andn2_b64 vcc, exec, s[22:23]
	s_cbranch_vccnz .LBB0_947
	s_barrier
	s_branch .LBB0_947
